# v28 with the sc1 scope bit on the SwiGLU activation stores
# speedup vs baseline: 1.0029x; 1.0029x over previous
.LBB0_436:
	s_add_u32 s30, s28, 0xfffc0080
	s_addc_u32 s31, s29, -1
	s_add_i32 s46, 0, 0x10000
	s_cmp_eq_u32 s56, 12
	s_cselect_b32 s35, s21, s31
	s_cselect_b32 s34, s51, s30
	v_add_u32_e32 v149, s46, v147
	s_cselect_b32 s31, s7, s55
	s_cselect_b32 s30, s53, s54
	s_add_i32 s58, 0, 0x14000
	ds_read_b128 v[142:145], v149
	ds_read_b128 v[150:153], v149 offset:1024
	ds_read_b128 v[154:157], v149 offset:2048
	ds_read_b128 v[158:161], v149 offset:3072
	v_add_u32_e32 v149, s58, v147
	ds_read_b128 v[162:165], v149
	ds_read_b128 v[166:169], v149 offset:1024
	ds_read_b128 v[170:173], v149 offset:2048
	ds_read_b128 v[174:177], v149 offset:3072
	v_lshl_add_u64 v[178:179], s[28:29], 0, v[138:139]
	s_add_i32 m0, s5, 0xc000
	ds_read_b128 v[190:193], v148
	ds_read_b128 v[194:197], v148 offset:1024
	ds_read_b128 v[198:201], v148 offset:2048
	ds_read_b128 v[202:205], v148 offset:3072
	ds_read_b128 v[206:209], v148 offset:4096
	ds_read_b128 v[210:213], v148 offset:5120
	ds_read_b128 v[214:217], v148 offset:6144
	ds_read_b128 v[228:231], v148 offset:7168
	global_load_lds_dwordx4 v[178:179], off
	v_lshl_add_u64 v[178:179], s[28:29], 0, v[140:141]
	s_add_i32 m0, s5, 0xe000
	s_nop 0
	global_load_lds_dwordx4 v[178:179], off
	s_waitcnt vmcnt(8)
	s_waitcnt lgkmcnt(0)
	s_barrier
	s_setprio 1
	s_waitcnt lgkmcnt(0)
	v_mfma_f32_16x16x32_bf16 v[128:131], v[142:145], v[190:193], v[128:131]
	v_mfma_f32_16x16x32_bf16 v[120:123], v[154:157], v[190:193], v[120:123]
	v_mfma_f32_16x16x32_bf16 v[112:115], v[142:145], v[198:201], v[112:115]
	v_mfma_f32_16x16x32_bf16 v[104:107], v[154:157], v[198:201], v[104:107]
	v_mfma_f32_16x16x32_bf16 v[96:99], v[142:145], v[206:209], v[96:99]
	v_mfma_f32_16x16x32_bf16 v[88:91], v[154:157], v[206:209], v[88:91]
	v_mfma_f32_16x16x32_bf16 v[80:83], v[142:145], v[214:217], v[80:83]
	v_mfma_f32_16x16x32_bf16 v[72:75], v[154:157], v[214:217], v[72:75]
	v_mfma_f32_16x16x32_bf16 v[128:131], v[150:153], v[194:197], v[128:131]
	v_mfma_f32_16x16x32_bf16 v[120:123], v[158:161], v[194:197], v[120:123]
	v_mfma_f32_16x16x32_bf16 v[112:115], v[150:153], v[202:205], v[112:115]
	v_mfma_f32_16x16x32_bf16 v[104:107], v[158:161], v[202:205], v[104:107]
	v_mfma_f32_16x16x32_bf16 v[96:99], v[150:153], v[210:213], v[96:99]
	v_mfma_f32_16x16x32_bf16 v[88:91], v[158:161], v[210:213], v[88:91]
	v_mfma_f32_16x16x32_bf16 v[80:83], v[150:153], v[228:231], v[80:83]
	v_mfma_f32_16x16x32_bf16 v[72:75], v[158:161], v[228:231], v[72:75]
	s_setprio 0
	s_setprio 1
	v_mfma_f32_16x16x32_bf16 v[124:127], v[162:165], v[190:193], v[124:127]
	v_mfma_f32_16x16x32_bf16 v[116:119], v[170:173], v[190:193], v[116:119]
	v_mfma_f32_16x16x32_bf16 v[108:111], v[162:165], v[198:201], v[108:111]
	v_mfma_f32_16x16x32_bf16 v[100:103], v[170:173], v[198:201], v[100:103]
	v_mfma_f32_16x16x32_bf16 v[92:95], v[162:165], v[206:209], v[92:95]
	v_mfma_f32_16x16x32_bf16 v[84:87], v[170:173], v[206:209], v[84:87]
	v_mfma_f32_16x16x32_bf16 v[76:79], v[162:165], v[214:217], v[76:79]
	v_mfma_f32_16x16x32_bf16 v[68:71], v[170:173], v[214:217], v[68:71]
	v_mfma_f32_16x16x32_bf16 v[124:127], v[166:169], v[194:197], v[124:127]
	v_mfma_f32_16x16x32_bf16 v[116:119], v[174:177], v[194:197], v[116:119]
	v_mfma_f32_16x16x32_bf16 v[108:111], v[166:169], v[202:205], v[108:111]
	v_mfma_f32_16x16x32_bf16 v[100:103], v[174:177], v[202:205], v[100:103]
	v_mfma_f32_16x16x32_bf16 v[92:95], v[166:169], v[210:213], v[92:95]
	v_mfma_f32_16x16x32_bf16 v[84:87], v[174:177], v[210:213], v[84:87]
	v_mfma_f32_16x16x32_bf16 v[76:79], v[166:169], v[228:231], v[76:79]
	v_mfma_f32_16x16x32_bf16 v[68:71], v[174:177], v[228:231], v[68:71]
	s_setprio 0
	s_barrier
	s_add_i32 s46, s46, s16
	v_lshl_add_u64 v[178:179], s[30:31], 0, v[184:185]
	s_mov_b32 m0, s46
	ds_read_b128 v[190:193], v148 offset:16384
	ds_read_b128 v[194:197], v148 offset:17408
	ds_read_b128 v[198:201], v148 offset:18432
	ds_read_b128 v[202:205], v148 offset:19456
	ds_read_b128 v[206:209], v148 offset:20480
	ds_read_b128 v[210:213], v148 offset:21504
	ds_read_b128 v[214:217], v148 offset:22528
	ds_read_b128 v[228:231], v148 offset:23552
	global_load_lds_dwordx4 v[178:179], off
	s_add_i32 m0, s46, 0x2000
	s_add_u32 s46, s30, 0x40000
	v_lshl_add_u64 v[218:219], s[30:31], 0, v[132:133]
	s_addc_u32 s47, s31, 0
	s_add_i32 s58, s58, s16
	global_load_lds_dwordx4 v[218:219], off
	v_lshl_add_u64 v[232:233], s[46:47], 0, v[184:185]
	s_mov_b32 m0, s58
	v_lshl_add_u64 v[234:235], s[34:35], 0, v[134:135]
	global_load_lds_dwordx4 v[232:233], off
	v_lshl_add_u64 v[232:233], s[46:47], 0, v[132:133]
	s_add_i32 m0, s58, 0x2000
	s_nop 0
	global_load_lds_dwordx4 v[232:233], off
	v_lshl_add_u64 v[232:233], s[34:35], 0, v[136:137]
	s_mov_b32 m0, s5
	s_nop 0
	global_load_lds_dwordx4 v[232:233], off
	s_mov_b32 m0, s23
	s_nop 0
	global_load_lds_dwordx4 v[234:235], off
	s_waitcnt vmcnt(8)
	s_waitcnt lgkmcnt(0)
	s_barrier
	s_setprio 1
	s_waitcnt lgkmcnt(0)
	v_mfma_f32_16x16x32_bf16 v[62:65], v[142:145], v[190:193], v[62:65]
	v_mfma_f32_16x16x32_bf16 v[54:57], v[154:157], v[190:193], v[54:57]
	v_mfma_f32_16x16x32_bf16 v[46:49], v[142:145], v[198:201], v[46:49]
	v_mfma_f32_16x16x32_bf16 v[38:41], v[154:157], v[198:201], v[38:41]
	v_mfma_f32_16x16x32_bf16 v[30:33], v[142:145], v[206:209], v[30:33]
	v_mfma_f32_16x16x32_bf16 v[22:25], v[154:157], v[206:209], v[22:25]
	v_mfma_f32_16x16x32_bf16 v[14:17], v[142:145], v[214:217], v[14:17]
	v_mfma_f32_16x16x32_bf16 v[6:9], v[154:157], v[214:217], v[6:9]
	v_mfma_f32_16x16x32_bf16 v[62:65], v[150:153], v[194:197], v[62:65]
	v_mfma_f32_16x16x32_bf16 v[54:57], v[158:161], v[194:197], v[54:57]
	v_mfma_f32_16x16x32_bf16 v[46:49], v[150:153], v[202:205], v[46:49]
	v_mfma_f32_16x16x32_bf16 v[38:41], v[158:161], v[202:205], v[38:41]
	v_mfma_f32_16x16x32_bf16 v[30:33], v[150:153], v[210:213], v[30:33]
	v_mfma_f32_16x16x32_bf16 v[22:25], v[158:161], v[210:213], v[22:25]
	v_mfma_f32_16x16x32_bf16 v[14:17], v[150:153], v[228:231], v[14:17]
	v_mfma_f32_16x16x32_bf16 v[6:9], v[158:161], v[228:231], v[6:9]
	s_setprio 0
	s_setprio 1
	v_mfma_f32_16x16x32_bf16 v[58:61], v[162:165], v[190:193], v[58:61]
	v_mfma_f32_16x16x32_bf16 v[50:53], v[170:173], v[190:193], v[50:53]
	v_mfma_f32_16x16x32_bf16 v[42:45], v[162:165], v[198:201], v[42:45]
	v_mfma_f32_16x16x32_bf16 v[34:37], v[170:173], v[198:201], v[34:37]
	v_mfma_f32_16x16x32_bf16 v[26:29], v[162:165], v[206:209], v[26:29]
	v_mfma_f32_16x16x32_bf16 v[18:21], v[170:173], v[206:209], v[18:21]
	v_mfma_f32_16x16x32_bf16 v[10:13], v[162:165], v[214:217], v[10:13]
	v_mfma_f32_16x16x32_bf16 v[2:5], v[170:173], v[214:217], v[2:5]
	v_mfma_f32_16x16x32_bf16 v[58:61], v[166:169], v[194:197], v[58:61]
	v_mfma_f32_16x16x32_bf16 v[50:53], v[174:177], v[194:197], v[50:53]
	v_mfma_f32_16x16x32_bf16 v[42:45], v[166:169], v[202:205], v[42:45]
	v_mfma_f32_16x16x32_bf16 v[34:37], v[174:177], v[202:205], v[34:37]
	v_mfma_f32_16x16x32_bf16 v[26:29], v[166:169], v[210:213], v[26:29]
	v_mfma_f32_16x16x32_bf16 v[18:21], v[174:177], v[210:213], v[18:21]
	v_mfma_f32_16x16x32_bf16 v[10:13], v[166:169], v[228:231], v[10:13]
	v_mfma_f32_16x16x32_bf16 v[2:5], v[174:177], v[228:231], v[2:5]
	s_setprio 0
	s_barrier
	s_add_i32 s46, 0, 0x18000
	v_add_u32_e32 v149, s46, v147
	s_add_i32 s47, 0, 0x1c000
	ds_read_b128 v[142:145], v149
	ds_read_b128 v[150:153], v149 offset:1024
	ds_read_b128 v[154:157], v149 offset:2048
	ds_read_b128 v[158:161], v149 offset:3072
	v_add_u32_e32 v149, s47, v147
	ds_read_b128 v[162:165], v149
	ds_read_b128 v[166:169], v149 offset:1024
	ds_read_b128 v[170:173], v149 offset:2048
	ds_read_b128 v[174:177], v149 offset:3072
	s_add_u32 s34, s34, 0x40000
	s_addc_u32 s35, s35, 0
	s_mov_b32 m0, s24
	v_lshl_add_u64 v[236:237], s[34:35], 0, v[136:137]
	ds_read_b128 v[190:193], v148 offset:32768
	ds_read_b128 v[194:197], v148 offset:33792
	ds_read_b128 v[198:201], v148 offset:34816
	ds_read_b128 v[202:205], v148 offset:35840
	ds_read_b128 v[206:209], v148 offset:36864
	ds_read_b128 v[210:213], v148 offset:37888
	ds_read_b128 v[214:217], v148 offset:38912
	ds_read_b128 v[228:231], v148 offset:39936
	global_load_lds_dwordx4 v[236:237], off
	v_lshl_add_u64 v[236:237], s[34:35], 0, v[134:135]
	s_mov_b32 m0, s25
	s_nop 0
	global_load_lds_dwordx4 v[236:237], off
	s_waitcnt vmcnt(8)
	s_waitcnt lgkmcnt(0)
	s_barrier
	s_setprio 1
	s_waitcnt lgkmcnt(0)
	v_mfma_f32_16x16x32_bf16 v[128:131], v[142:145], v[190:193], v[128:131]
	v_mfma_f32_16x16x32_bf16 v[120:123], v[154:157], v[190:193], v[120:123]
	v_mfma_f32_16x16x32_bf16 v[112:115], v[142:145], v[198:201], v[112:115]
	v_mfma_f32_16x16x32_bf16 v[104:107], v[154:157], v[198:201], v[104:107]
	v_mfma_f32_16x16x32_bf16 v[96:99], v[142:145], v[206:209], v[96:99]
	v_mfma_f32_16x16x32_bf16 v[88:91], v[154:157], v[206:209], v[88:91]
	v_mfma_f32_16x16x32_bf16 v[80:83], v[142:145], v[214:217], v[80:83]
	v_mfma_f32_16x16x32_bf16 v[72:75], v[154:157], v[214:217], v[72:75]
	v_mfma_f32_16x16x32_bf16 v[128:131], v[150:153], v[194:197], v[128:131]
	v_mfma_f32_16x16x32_bf16 v[120:123], v[158:161], v[194:197], v[120:123]
	v_mfma_f32_16x16x32_bf16 v[112:115], v[150:153], v[202:205], v[112:115]
	v_mfma_f32_16x16x32_bf16 v[104:107], v[158:161], v[202:205], v[104:107]
	v_mfma_f32_16x16x32_bf16 v[96:99], v[150:153], v[210:213], v[96:99]
	v_mfma_f32_16x16x32_bf16 v[88:91], v[158:161], v[210:213], v[88:91]
	v_mfma_f32_16x16x32_bf16 v[80:83], v[150:153], v[228:231], v[80:83]
	v_mfma_f32_16x16x32_bf16 v[72:75], v[158:161], v[228:231], v[72:75]
	s_setprio 0
	s_setprio 1
	v_mfma_f32_16x16x32_bf16 v[124:127], v[162:165], v[190:193], v[124:127]
	v_mfma_f32_16x16x32_bf16 v[116:119], v[170:173], v[190:193], v[116:119]
	v_mfma_f32_16x16x32_bf16 v[108:111], v[162:165], v[198:201], v[108:111]
	v_mfma_f32_16x16x32_bf16 v[100:103], v[170:173], v[198:201], v[100:103]
	v_mfma_f32_16x16x32_bf16 v[92:95], v[162:165], v[206:209], v[92:95]
	v_mfma_f32_16x16x32_bf16 v[84:87], v[170:173], v[206:209], v[84:87]
	v_mfma_f32_16x16x32_bf16 v[76:79], v[162:165], v[214:217], v[76:79]
	v_mfma_f32_16x16x32_bf16 v[68:71], v[170:173], v[214:217], v[68:71]
	v_mfma_f32_16x16x32_bf16 v[124:127], v[166:169], v[194:197], v[124:127]
	v_mfma_f32_16x16x32_bf16 v[116:119], v[174:177], v[194:197], v[116:119]
	v_mfma_f32_16x16x32_bf16 v[108:111], v[166:169], v[202:205], v[108:111]
	v_mfma_f32_16x16x32_bf16 v[100:103], v[174:177], v[202:205], v[100:103]
	v_mfma_f32_16x16x32_bf16 v[92:95], v[166:169], v[210:213], v[92:95]
	v_mfma_f32_16x16x32_bf16 v[84:87], v[174:177], v[210:213], v[84:87]
	v_mfma_f32_16x16x32_bf16 v[76:79], v[166:169], v[228:231], v[76:79]
	v_mfma_f32_16x16x32_bf16 v[68:71], v[174:177], v[228:231], v[68:71]
	s_setprio 0
	s_barrier
	s_add_i32 s34, s46, s16
	v_lshl_add_u64 v[178:179], v[178:179], 0, s[18:19]
	s_mov_b32 m0, s34
	ds_read_b128 v[190:193], v148 offset:49152
	ds_read_b128 v[194:197], v148 offset:50176
	ds_read_b128 v[198:201], v148 offset:51200
	ds_read_b128 v[202:205], v148 offset:52224
	ds_read_b128 v[206:209], v148 offset:53248
	ds_read_b128 v[210:213], v148 offset:54272
	ds_read_b128 v[214:217], v148 offset:55296
	ds_read_b128 v[228:231], v148 offset:56320
	global_load_lds_dwordx4 v[178:179], off
	s_add_i32 m0, s34, 0x2000
	s_add_u32 s30, s30, 0x40080
	v_lshl_add_u64 v[178:179], v[218:219], 0, s[18:19]
	s_addc_u32 s31, s31, 0
	s_add_i32 s34, s47, s16
	global_load_lds_dwordx4 v[178:179], off
	v_lshl_add_u64 v[178:179], s[30:31], 0, v[184:185]
	s_mov_b32 m0, s34
	s_nop 0
	global_load_lds_dwordx4 v[178:179], off
	v_lshl_add_u64 v[178:179], s[30:31], 0, v[132:133]
	s_add_i32 m0, s34, 0x2000
	s_nop 0
	global_load_lds_dwordx4 v[178:179], off
	v_lshl_add_u64 v[178:179], v[232:233], 0, s[18:19]
	s_mov_b32 m0, s42
	s_nop 0
	global_load_lds_dwordx4 v[178:179], off
	v_lshl_add_u64 v[178:179], v[234:235], 0, s[18:19]
	s_mov_b32 m0, s43
	s_nop 0
	global_load_lds_dwordx4 v[178:179], off
	s_waitcnt vmcnt(8)
	s_waitcnt lgkmcnt(0)
	s_barrier
	s_setprio 1
	s_waitcnt lgkmcnt(0)
	v_mfma_f32_16x16x32_bf16 v[62:65], v[142:145], v[190:193], v[62:65]
	v_mfma_f32_16x16x32_bf16 v[54:57], v[154:157], v[190:193], v[54:57]
	v_mfma_f32_16x16x32_bf16 v[46:49], v[142:145], v[198:201], v[46:49]
	v_mfma_f32_16x16x32_bf16 v[38:41], v[154:157], v[198:201], v[38:41]
	v_mfma_f32_16x16x32_bf16 v[30:33], v[142:145], v[206:209], v[30:33]
	v_mfma_f32_16x16x32_bf16 v[22:25], v[154:157], v[206:209], v[22:25]
	v_mfma_f32_16x16x32_bf16 v[14:17], v[142:145], v[214:217], v[14:17]
	v_mfma_f32_16x16x32_bf16 v[6:9], v[154:157], v[214:217], v[6:9]
	v_mfma_f32_16x16x32_bf16 v[62:65], v[150:153], v[194:197], v[62:65]
	v_mfma_f32_16x16x32_bf16 v[54:57], v[158:161], v[194:197], v[54:57]
	v_mfma_f32_16x16x32_bf16 v[46:49], v[150:153], v[202:205], v[46:49]
	v_mfma_f32_16x16x32_bf16 v[38:41], v[158:161], v[202:205], v[38:41]
	v_mfma_f32_16x16x32_bf16 v[30:33], v[150:153], v[210:213], v[30:33]
	v_mfma_f32_16x16x32_bf16 v[22:25], v[158:161], v[210:213], v[22:25]
	v_mfma_f32_16x16x32_bf16 v[14:17], v[150:153], v[228:231], v[14:17]
	v_mfma_f32_16x16x32_bf16 v[6:9], v[158:161], v[228:231], v[6:9]
	s_setprio 0
	s_setprio 1
	v_mfma_f32_16x16x32_bf16 v[58:61], v[162:165], v[190:193], v[58:61]
	v_mfma_f32_16x16x32_bf16 v[50:53], v[170:173], v[190:193], v[50:53]
	v_mfma_f32_16x16x32_bf16 v[42:45], v[162:165], v[198:201], v[42:45]
	v_mfma_f32_16x16x32_bf16 v[34:37], v[170:173], v[198:201], v[34:37]
	v_mfma_f32_16x16x32_bf16 v[26:29], v[162:165], v[206:209], v[26:29]
	v_mfma_f32_16x16x32_bf16 v[18:21], v[170:173], v[206:209], v[18:21]
	v_mfma_f32_16x16x32_bf16 v[10:13], v[162:165], v[214:217], v[10:13]
	v_mfma_f32_16x16x32_bf16 v[2:5], v[170:173], v[214:217], v[2:5]
	v_mfma_f32_16x16x32_bf16 v[58:61], v[166:169], v[194:197], v[58:61]
	v_mfma_f32_16x16x32_bf16 v[50:53], v[174:177], v[194:197], v[50:53]
	v_mfma_f32_16x16x32_bf16 v[42:45], v[166:169], v[202:205], v[42:45]
	v_mfma_f32_16x16x32_bf16 v[34:37], v[174:177], v[202:205], v[34:37]
	v_mfma_f32_16x16x32_bf16 v[26:29], v[166:169], v[210:213], v[26:29]
	v_mfma_f32_16x16x32_bf16 v[18:21], v[174:177], v[210:213], v[18:21]
	v_mfma_f32_16x16x32_bf16 v[10:13], v[166:169], v[228:231], v[10:13]
	v_mfma_f32_16x16x32_bf16 v[2:5], v[174:177], v[228:231], v[2:5]
	s_setprio 0
	s_barrier
	s_add_i32 s56, s56, 2
	s_add_u32 s28, s28, 0x100
	s_addc_u32 s29, s29, 0
	s_add_u32 s54, s54, 0x100
	s_addc_u32 s55, s55, 0
	s_cmp_gt_u32 s56, 13
	s_cbranch_scc0 .LBB0_436
	v_mul_f32_e32 v152, 0xbfb8aa3b, v128
	v_mul_f32_e32 v153, 0xbfb8aa3b, v129
	v_exp_f32_e32 v152, v152
	v_exp_f32_e32 v153, v153
	s_lshl_b32 s4, s4, 8
	s_lshl_b32 s7, s50, 7
	v_add_f32_e32 v152, 1.0, v152
	v_add_f32_e32 v153, 1.0, v153
	v_rcp_f32_e32 v152, v152
	v_rcp_f32_e32 v153, v153
	v_mov_b32_e32 v142, v67
	v_mov_b32_e32 v143, v146
	s_or_b32 s7, s7, s41
	v_pk_mul_f32 v[128:129], v[128:129], v[152:153]
	s_add_i32 s4, s4, s40
	v_pk_mul_f32 v[124:125], v[128:129], v[124:125]
	s_and_b64 vcc, exec, s[38:39]
	v_cvt_pk_bf16_f32 v124, v124, v125
	v_mul_f32_e32 v125, 0xbfb8aa3b, v130
	v_exp_f32_e32 v125, v125
	v_lshl_add_u32 v144, v143, 3, s7
	v_add_u32_e32 v149, s4, v142
	v_ashrrev_i32_e32 v145, 31, v144
	v_add_f32_e32 v125, 1.0, v125
	v_rcp_f32_e32 v128, v125
	v_mul_f32_e32 v125, 0xbfb8aa3b, v131
	v_exp_f32_e32 v125, v125
	v_mov_b64_e32 v[142:143], s[80:81]
	v_mad_i64_i32 v[150:151], s[28:29], v149, s59, v[142:143]
	v_add_f32_e32 v125, 1.0, v125
	v_rcp_f32_e32 v129, v125
	v_lshlrev_b64 v[144:145], 1, v[144:145]
	v_lshl_add_u64 v[150:151], v[150:151], 0, v[144:145]
	s_mov_b32 s50, s6
	v_pk_mul_f32 v[128:129], v[130:131], v[128:129]
	s_mov_b32 s4, s20
	v_pk_mul_f32 v[126:127], v[128:129], v[126:127]
	s_mov_b64 s[30:31], s[36:37]
	v_cvt_pk_bf16_f32 v125, v126, v127
	v_mul_f32_e32 v126, 0xbfb8aa3b, v120
	v_mul_f32_e32 v127, 0xbfb8aa3b, v121
	v_exp_f32_e32 v126, v126
	v_exp_f32_e32 v127, v127
	v_add_f32_e32 v126, 1.0, v126
	v_add_f32_e32 v127, 1.0, v127
	v_rcp_f32_e32 v126, v126
	v_rcp_f32_e32 v127, v127
	s_nop 0
	v_pk_mul_f32 v[120:121], v[120:121], v[126:127]
	s_nop 0
	v_pk_mul_f32 v[116:117], v[120:121], v[116:117]
	s_nop 0
	v_cvt_pk_bf16_f32 v126, v116, v117
	v_mul_f32_e32 v116, 0xbfb8aa3b, v122
	v_mul_f32_e32 v117, 0xbfb8aa3b, v123
	v_exp_f32_e32 v116, v116
	v_exp_f32_e32 v117, v117
	v_add_f32_e32 v116, 1.0, v116
	v_add_f32_e32 v117, 1.0, v117
	v_rcp_f32_e32 v116, v116
	v_rcp_f32_e32 v117, v117
	s_nop 0
	v_pk_mul_f32 v[116:117], v[122:123], v[116:117]
	s_nop 0
	v_pk_mul_f32 v[116:117], v[116:117], v[118:119]
	v_mul_f32_e32 v118, 0xbfb8aa3b, v112
	v_mul_f32_e32 v119, 0xbfb8aa3b, v113
	v_exp_f32_e32 v118, v118
	v_exp_f32_e32 v119, v119
	v_cvt_pk_bf16_f32 v127, v116, v117
	v_add_u32_e32 v116, 16, v149
	v_add_f32_e32 v118, 1.0, v118
	v_add_f32_e32 v119, 1.0, v119
	v_rcp_f32_e32 v118, v118
	v_rcp_f32_e32 v119, v119
	v_mad_i64_i32 v[116:117], s[28:29], v116, s59, v[142:143]
	v_lshl_add_u64 v[116:117], v[116:117], 0, v[144:145]
	v_pk_mul_f32 v[112:113], v[112:113], v[118:119]
	global_store_dwordx4 v[150:151], v[124:127], off sc1
	v_pk_mul_f32 v[108:109], v[112:113], v[108:109]
	s_nop 0
	v_cvt_pk_bf16_f32 v108, v108, v109
	v_mul_f32_e32 v109, 0xbfb8aa3b, v114
	v_exp_f32_e32 v109, v109
	s_nop 0
	v_add_f32_e32 v109, 1.0, v109
	v_rcp_f32_e32 v112, v109
	v_mul_f32_e32 v109, 0xbfb8aa3b, v115
	v_exp_f32_e32 v109, v109
	s_nop 0
	v_add_f32_e32 v109, 1.0, v109
	v_rcp_f32_e32 v113, v109
	s_nop 0
	v_pk_mul_f32 v[112:113], v[114:115], v[112:113]
	s_nop 0
	v_pk_mul_f32 v[110:111], v[112:113], v[110:111]
	s_nop 0
	v_cvt_pk_bf16_f32 v109, v110, v111
	v_mul_f32_e32 v110, 0xbfb8aa3b, v104
	v_mul_f32_e32 v111, 0xbfb8aa3b, v105
	v_exp_f32_e32 v110, v110
	v_exp_f32_e32 v111, v111
	v_add_f32_e32 v110, 1.0, v110
	v_add_f32_e32 v111, 1.0, v111
	v_rcp_f32_e32 v110, v110
	v_rcp_f32_e32 v111, v111
	s_nop 0
	v_pk_mul_f32 v[104:105], v[104:105], v[110:111]
	s_nop 0
	v_pk_mul_f32 v[100:101], v[104:105], v[100:101]
	s_nop 0
	v_cvt_pk_bf16_f32 v110, v100, v101
	v_mul_f32_e32 v100, 0xbfb8aa3b, v106
	v_mul_f32_e32 v101, 0xbfb8aa3b, v107
	v_exp_f32_e32 v100, v100
	v_exp_f32_e32 v101, v101
	v_add_f32_e32 v100, 1.0, v100
	v_add_f32_e32 v101, 1.0, v101
	v_rcp_f32_e32 v100, v100
	v_rcp_f32_e32 v101, v101
	s_nop 0
	v_pk_mul_f32 v[100:101], v[106:107], v[100:101]
	s_nop 0
	v_pk_mul_f32 v[100:101], v[100:101], v[102:103]
	v_mul_f32_e32 v102, 0xbfb8aa3b, v96
	v_mul_f32_e32 v103, 0xbfb8aa3b, v97
	v_exp_f32_e32 v102, v102
	v_exp_f32_e32 v103, v103
	v_cvt_pk_bf16_f32 v111, v100, v101
	v_add_u32_e32 v100, 32, v149
	v_add_f32_e32 v102, 1.0, v102
	v_add_f32_e32 v103, 1.0, v103
	v_rcp_f32_e32 v102, v102
	v_rcp_f32_e32 v103, v103
	v_mad_i64_i32 v[100:101], s[28:29], v100, s59, v[142:143]
	v_lshl_add_u64 v[100:101], v[100:101], 0, v[144:145]
	v_pk_mul_f32 v[96:97], v[96:97], v[102:103]
	global_store_dwordx4 v[116:117], v[108:111], off sc1
	v_pk_mul_f32 v[92:93], v[96:97], v[92:93]
	s_nop 0
	v_cvt_pk_bf16_f32 v92, v92, v93
	v_mul_f32_e32 v93, 0xbfb8aa3b, v98
	v_exp_f32_e32 v93, v93
	s_nop 0
	v_add_f32_e32 v93, 1.0, v93
	v_rcp_f32_e32 v96, v93
	v_mul_f32_e32 v93, 0xbfb8aa3b, v99
	v_exp_f32_e32 v93, v93
	s_nop 0
	v_add_f32_e32 v93, 1.0, v93
	v_rcp_f32_e32 v97, v93
	s_nop 0
	v_pk_mul_f32 v[96:97], v[98:99], v[96:97]
	s_nop 0
	v_pk_mul_f32 v[94:95], v[96:97], v[94:95]
	s_nop 0
	v_cvt_pk_bf16_f32 v93, v94, v95
	v_mul_f32_e32 v94, 0xbfb8aa3b, v88
	v_mul_f32_e32 v95, 0xbfb8aa3b, v89
	v_exp_f32_e32 v94, v94
	v_exp_f32_e32 v95, v95
	v_add_f32_e32 v94, 1.0, v94
	v_add_f32_e32 v95, 1.0, v95
	v_rcp_f32_e32 v94, v94
	v_rcp_f32_e32 v95, v95
	s_nop 0
	v_pk_mul_f32 v[88:89], v[88:89], v[94:95]
	s_nop 0
	v_pk_mul_f32 v[84:85], v[88:89], v[84:85]
	s_nop 0
	v_cvt_pk_bf16_f32 v94, v84, v85
	v_mul_f32_e32 v84, 0xbfb8aa3b, v90
	v_mul_f32_e32 v85, 0xbfb8aa3b, v91
	v_exp_f32_e32 v84, v84
	v_exp_f32_e32 v85, v85
	v_add_f32_e32 v84, 1.0, v84
	v_add_f32_e32 v85, 1.0, v85
	v_rcp_f32_e32 v84, v84
	v_rcp_f32_e32 v85, v85
	s_nop 0
	v_pk_mul_f32 v[84:85], v[90:91], v[84:85]
	s_nop 0
	v_pk_mul_f32 v[84:85], v[84:85], v[86:87]
	v_mul_f32_e32 v86, 0xbfb8aa3b, v80
	v_mul_f32_e32 v87, 0xbfb8aa3b, v81
	v_exp_f32_e32 v86, v86
	v_exp_f32_e32 v87, v87
	v_cvt_pk_bf16_f32 v95, v84, v85
	v_add_u32_e32 v84, 48, v149
	v_add_f32_e32 v86, 1.0, v86
	v_add_f32_e32 v87, 1.0, v87
	v_rcp_f32_e32 v86, v86
	v_rcp_f32_e32 v87, v87
	v_mad_i64_i32 v[84:85], s[28:29], v84, s59, v[142:143]
	v_lshl_add_u64 v[84:85], v[84:85], 0, v[144:145]
	v_pk_mul_f32 v[80:81], v[80:81], v[86:87]
	global_store_dwordx4 v[100:101], v[92:95], off sc1
	v_pk_mul_f32 v[76:77], v[80:81], v[76:77]
	s_nop 0
	v_cvt_pk_bf16_f32 v76, v76, v77
	v_mul_f32_e32 v77, 0xbfb8aa3b, v82
	v_exp_f32_e32 v77, v77
	s_nop 0
	v_add_f32_e32 v77, 1.0, v77
	v_rcp_f32_e32 v80, v77
	v_mul_f32_e32 v77, 0xbfb8aa3b, v83
	v_exp_f32_e32 v77, v77
	s_nop 0
	v_add_f32_e32 v77, 1.0, v77
	v_rcp_f32_e32 v81, v77
	s_nop 0
	v_pk_mul_f32 v[80:81], v[82:83], v[80:81]
	s_nop 0
	v_pk_mul_f32 v[78:79], v[80:81], v[78:79]
	s_nop 0
	v_cvt_pk_bf16_f32 v77, v78, v79
	v_mul_f32_e32 v78, 0xbfb8aa3b, v72
	v_mul_f32_e32 v79, 0xbfb8aa3b, v73
	v_exp_f32_e32 v78, v78
	v_exp_f32_e32 v79, v79
	v_add_f32_e32 v78, 1.0, v78
	v_add_f32_e32 v79, 1.0, v79
	v_rcp_f32_e32 v78, v78
	v_rcp_f32_e32 v79, v79
	s_nop 0
	v_pk_mul_f32 v[72:73], v[72:73], v[78:79]
	s_nop 0
	v_pk_mul_f32 v[68:69], v[72:73], v[68:69]
	s_nop 0
	v_cvt_pk_bf16_f32 v78, v68, v69
	v_mul_f32_e32 v68, 0xbfb8aa3b, v74
	v_mul_f32_e32 v69, 0xbfb8aa3b, v75
	v_exp_f32_e32 v68, v68
	v_exp_f32_e32 v69, v69
	v_add_f32_e32 v68, 1.0, v68
	v_add_f32_e32 v69, 1.0, v69
	v_rcp_f32_e32 v68, v68
	v_rcp_f32_e32 v69, v69
	s_nop 0
	v_pk_mul_f32 v[68:69], v[74:75], v[68:69]
	s_nop 0
	v_pk_mul_f32 v[68:69], v[68:69], v[70:71]
	v_mul_f32_e32 v70, 0xbfb8aa3b, v62
	v_mul_f32_e32 v71, 0xbfb8aa3b, v63
	v_exp_f32_e32 v70, v70
	v_exp_f32_e32 v71, v71
	v_cvt_pk_bf16_f32 v79, v68, v69
	v_add_u32_e32 v68, 0x80, v149
	v_add_f32_e32 v70, 1.0, v70
	v_add_f32_e32 v71, 1.0, v71
	v_rcp_f32_e32 v70, v70
	v_rcp_f32_e32 v71, v71
	v_mad_i64_i32 v[68:69], s[28:29], v68, s59, v[142:143]
	v_lshl_add_u64 v[68:69], v[68:69], 0, v[144:145]
	v_pk_mul_f32 v[62:63], v[62:63], v[70:71]
	global_store_dwordx4 v[84:85], v[76:79], off sc1
	v_pk_mul_f32 v[58:59], v[62:63], v[58:59]
	s_nop 0
	v_cvt_pk_bf16_f32 v58, v58, v59
	v_mul_f32_e32 v59, 0xbfb8aa3b, v64
	v_exp_f32_e32 v59, v59
	s_nop 0
	v_add_f32_e32 v59, 1.0, v59
	v_rcp_f32_e32 v62, v59
	v_mul_f32_e32 v59, 0xbfb8aa3b, v65
	v_exp_f32_e32 v59, v59
	s_nop 0
	v_add_f32_e32 v59, 1.0, v59
	v_rcp_f32_e32 v63, v59
	s_nop 0
	v_pk_mul_f32 v[62:63], v[64:65], v[62:63]
	s_nop 0
	v_pk_mul_f32 v[60:61], v[62:63], v[60:61]
	s_nop 0
	v_cvt_pk_bf16_f32 v59, v60, v61
	v_mul_f32_e32 v60, 0xbfb8aa3b, v54
	v_mul_f32_e32 v61, 0xbfb8aa3b, v55
	v_exp_f32_e32 v60, v60
	v_exp_f32_e32 v61, v61
	v_add_f32_e32 v60, 1.0, v60
	v_add_f32_e32 v61, 1.0, v61
	v_rcp_f32_e32 v60, v60
	v_rcp_f32_e32 v61, v61
	s_nop 0
	v_pk_mul_f32 v[54:55], v[54:55], v[60:61]
	s_nop 0
	v_pk_mul_f32 v[50:51], v[54:55], v[50:51]
	s_nop 0
	v_cvt_pk_bf16_f32 v60, v50, v51
	v_mul_f32_e32 v50, 0xbfb8aa3b, v56
	v_mul_f32_e32 v51, 0xbfb8aa3b, v57
	v_exp_f32_e32 v50, v50
	v_exp_f32_e32 v51, v51
	v_add_f32_e32 v50, 1.0, v50
	v_add_f32_e32 v51, 1.0, v51
	v_rcp_f32_e32 v50, v50
	v_rcp_f32_e32 v51, v51
	s_nop 0
	v_pk_mul_f32 v[50:51], v[56:57], v[50:51]
	s_nop 0
	v_pk_mul_f32 v[50:51], v[50:51], v[52:53]
	v_mul_f32_e32 v52, 0xbfb8aa3b, v46
	v_mul_f32_e32 v53, 0xbfb8aa3b, v47
	v_exp_f32_e32 v52, v52
	v_exp_f32_e32 v53, v53
	v_cvt_pk_bf16_f32 v61, v50, v51
	v_add_u32_e32 v50, 0x90, v149
	v_add_f32_e32 v52, 1.0, v52
	v_add_f32_e32 v53, 1.0, v53
	v_rcp_f32_e32 v52, v52
	v_rcp_f32_e32 v53, v53
	v_mad_i64_i32 v[50:51], s[28:29], v50, s59, v[142:143]
	v_lshl_add_u64 v[50:51], v[50:51], 0, v[144:145]
	v_pk_mul_f32 v[46:47], v[46:47], v[52:53]
	global_store_dwordx4 v[68:69], v[58:61], off sc1
	v_pk_mul_f32 v[42:43], v[46:47], v[42:43]
	s_nop 0
	v_cvt_pk_bf16_f32 v42, v42, v43
	v_mul_f32_e32 v43, 0xbfb8aa3b, v48
	v_exp_f32_e32 v43, v43
	s_nop 0
	v_add_f32_e32 v43, 1.0, v43
	v_rcp_f32_e32 v46, v43
	v_mul_f32_e32 v43, 0xbfb8aa3b, v49
	v_exp_f32_e32 v43, v43
	s_nop 0
	v_add_f32_e32 v43, 1.0, v43
	v_rcp_f32_e32 v47, v43
	s_nop 0
	v_pk_mul_f32 v[46:47], v[48:49], v[46:47]
	s_nop 0
	v_pk_mul_f32 v[44:45], v[46:47], v[44:45]
	s_nop 0
	v_cvt_pk_bf16_f32 v43, v44, v45
	v_mul_f32_e32 v44, 0xbfb8aa3b, v38
	v_mul_f32_e32 v45, 0xbfb8aa3b, v39
	v_exp_f32_e32 v44, v44
	v_exp_f32_e32 v45, v45
	v_add_f32_e32 v44, 1.0, v44
	v_add_f32_e32 v45, 1.0, v45
	v_rcp_f32_e32 v44, v44
	v_rcp_f32_e32 v45, v45
	s_nop 0
	v_pk_mul_f32 v[38:39], v[38:39], v[44:45]
	s_nop 0
	v_pk_mul_f32 v[34:35], v[38:39], v[34:35]
	s_nop 0
	v_cvt_pk_bf16_f32 v44, v34, v35
	v_mul_f32_e32 v34, 0xbfb8aa3b, v40
	v_mul_f32_e32 v35, 0xbfb8aa3b, v41
	v_exp_f32_e32 v34, v34
	v_exp_f32_e32 v35, v35
	v_add_f32_e32 v34, 1.0, v34
	v_add_f32_e32 v35, 1.0, v35
	v_rcp_f32_e32 v34, v34
	v_rcp_f32_e32 v35, v35
	s_nop 0
	v_pk_mul_f32 v[34:35], v[40:41], v[34:35]
	s_nop 0
	v_pk_mul_f32 v[34:35], v[34:35], v[36:37]
	v_mul_f32_e32 v36, 0xbfb8aa3b, v30
	v_mul_f32_e32 v37, 0xbfb8aa3b, v31
	v_exp_f32_e32 v36, v36
	v_exp_f32_e32 v37, v37
	v_cvt_pk_bf16_f32 v45, v34, v35
	v_add_u32_e32 v34, 0xa0, v149
	v_add_f32_e32 v36, 1.0, v36
	v_add_f32_e32 v37, 1.0, v37
	v_rcp_f32_e32 v36, v36
	v_rcp_f32_e32 v37, v37
	v_mad_i64_i32 v[34:35], s[28:29], v34, s59, v[142:143]
	v_lshl_add_u64 v[34:35], v[34:35], 0, v[144:145]
	v_pk_mul_f32 v[30:31], v[30:31], v[36:37]
	global_store_dwordx4 v[50:51], v[42:45], off sc1
	v_pk_mul_f32 v[26:27], v[30:31], v[26:27]
	s_nop 0
	v_cvt_pk_bf16_f32 v26, v26, v27
	v_mul_f32_e32 v27, 0xbfb8aa3b, v32
	v_exp_f32_e32 v27, v27
	s_nop 0
	v_add_f32_e32 v27, 1.0, v27
	v_rcp_f32_e32 v30, v27
	v_mul_f32_e32 v27, 0xbfb8aa3b, v33
	v_exp_f32_e32 v27, v27
	s_nop 0
	v_add_f32_e32 v27, 1.0, v27
	v_rcp_f32_e32 v31, v27
	s_nop 0
	v_pk_mul_f32 v[30:31], v[32:33], v[30:31]
	s_nop 0
	v_pk_mul_f32 v[28:29], v[30:31], v[28:29]
	s_nop 0
	v_cvt_pk_bf16_f32 v27, v28, v29
	v_mul_f32_e32 v28, 0xbfb8aa3b, v22
	v_mul_f32_e32 v29, 0xbfb8aa3b, v23
	v_exp_f32_e32 v28, v28
	v_exp_f32_e32 v29, v29
	v_add_f32_e32 v28, 1.0, v28
	v_add_f32_e32 v29, 1.0, v29
	v_rcp_f32_e32 v28, v28
	v_rcp_f32_e32 v29, v29
	s_nop 0
	v_pk_mul_f32 v[22:23], v[22:23], v[28:29]
	s_nop 0
	v_pk_mul_f32 v[18:19], v[22:23], v[18:19]
	s_nop 0
	v_cvt_pk_bf16_f32 v28, v18, v19
	v_mul_f32_e32 v18, 0xbfb8aa3b, v24
	v_mul_f32_e32 v19, 0xbfb8aa3b, v25
	v_exp_f32_e32 v18, v18
	v_exp_f32_e32 v19, v19
	v_add_f32_e32 v18, 1.0, v18
	v_add_f32_e32 v19, 1.0, v19
	v_rcp_f32_e32 v18, v18
	v_rcp_f32_e32 v19, v19
	s_nop 0
	v_pk_mul_f32 v[18:19], v[24:25], v[18:19]
	s_nop 0
	v_pk_mul_f32 v[18:19], v[18:19], v[20:21]
	v_mul_f32_e32 v20, 0xbfb8aa3b, v14
	v_mul_f32_e32 v21, 0xbfb8aa3b, v15
	v_exp_f32_e32 v20, v20
	v_exp_f32_e32 v21, v21
	v_cvt_pk_bf16_f32 v29, v18, v19
	v_add_u32_e32 v18, 0xb0, v149
	v_add_f32_e32 v20, 1.0, v20
	v_add_f32_e32 v21, 1.0, v21
	v_rcp_f32_e32 v20, v20
	v_rcp_f32_e32 v21, v21
	v_mad_i64_i32 v[18:19], s[28:29], v18, s59, v[142:143]
	v_lshl_add_u64 v[18:19], v[18:19], 0, v[144:145]
	v_pk_mul_f32 v[14:15], v[14:15], v[20:21]
	s_mov_b64 s[28:29], s[26:27]
	v_pk_mul_f32 v[10:11], v[14:15], v[10:11]
	global_store_dwordx4 v[34:35], v[26:29], off sc1
	v_cvt_pk_bf16_f32 v10, v10, v11
	v_mul_f32_e32 v11, 0xbfb8aa3b, v16
	v_exp_f32_e32 v11, v11
	s_nop 0
	v_add_f32_e32 v11, 1.0, v11
	v_rcp_f32_e32 v14, v11
	v_mul_f32_e32 v11, 0xbfb8aa3b, v17
	v_exp_f32_e32 v11, v11
	s_nop 0
	v_add_f32_e32 v11, 1.0, v11
	v_rcp_f32_e32 v15, v11
	s_nop 0
	v_pk_mul_f32 v[14:15], v[16:17], v[14:15]
	s_nop 0
	v_pk_mul_f32 v[12:13], v[14:15], v[12:13]
	s_nop 0
	v_cvt_pk_bf16_f32 v11, v12, v13
	v_mul_f32_e32 v12, 0xbfb8aa3b, v6
	v_mul_f32_e32 v13, 0xbfb8aa3b, v7
	v_exp_f32_e32 v12, v12
	v_exp_f32_e32 v13, v13
	v_add_f32_e32 v12, 1.0, v12
	v_add_f32_e32 v13, 1.0, v13
	v_rcp_f32_e32 v12, v12
	v_rcp_f32_e32 v13, v13
	s_nop 0
	v_pk_mul_f32 v[6:7], v[6:7], v[12:13]
	s_nop 0
	v_pk_mul_f32 v[2:3], v[6:7], v[2:3]
	s_nop 0
	v_cvt_pk_bf16_f32 v12, v2, v3
	v_mul_f32_e32 v2, 0xbfb8aa3b, v8
	v_mul_f32_e32 v3, 0xbfb8aa3b, v9
	v_exp_f32_e32 v2, v2
	v_exp_f32_e32 v3, v3
	v_add_f32_e32 v2, 1.0, v2
	v_add_f32_e32 v3, 1.0, v3
	v_rcp_f32_e32 v2, v2
	v_rcp_f32_e32 v3, v3
	s_nop 0
	v_pk_mul_f32 v[2:3], v[8:9], v[2:3]
	s_nop 0
	v_pk_mul_f32 v[2:3], v[2:3], v[4:5]
	s_nop 0
	v_cvt_pk_bf16_f32 v13, v2, v3
	global_store_dwordx4 v[18:19], v[10:13], off sc1
	s_cbranch_vccz .LBB0_433
	s_waitcnt vmcnt(0)
	s_cmpk_gt_u32 s1, 0xff
	s_cbranch_scc1 .LBB0_440
	s_barrier
